# P5 epilogue stores carry sc1 (write-through) so the grid barrier's L2 write-back before LayerNorm has little left to flush
# speedup vs baseline: 1.0070x; 1.0070x over previous
.LBB0_2585:
	s_lshl_b32 s12, s19, 2
	s_add_u32 s12, s4, s12
	s_addc_u32 s13, s5, 0
	s_lshl_b32 s14, s20, 2
	s_add_u32 s12, s12, s14
	s_addc_u32 s13, s13, 0
	v_mov_b32_e32 v75, v65
	v_lshl_add_u64 v[150:151], s[12:13], 0, v[74:75]
	s_waitcnt vmcnt(0)
	v_fmamk_f32 v48, v168, 0x3f9837f0, v48
	v_lshl_add_u64 v[78:79], v[150:151], 0, v[78:79]
	v_fmamk_f32 v32, v167, 0x3f9837f0, v32
	global_store_dword v[78:79], v48, off sc1
	global_store_dword v[78:79], v32, off offset:128 sc1
	v_fmamk_f32 v32, v166, 0x3f9837f0, v49
	v_lshl_add_u64 v[48:49], v[150:151], 0, v[80:81]
	global_store_dword v[48:49], v32, off sc1
	v_fmamk_f32 v32, v165, 0x3f9837f0, v33
	global_store_dword v[48:49], v32, off offset:128 sc1
	v_fmamk_f32 v48, v164, 0x3f9837f0, v50
	v_lshl_add_u64 v[32:33], v[150:151], 0, v[82:83]
	v_fmamk_f32 v34, v163, 0x3f9837f0, v34
	global_store_dword v[32:33], v48, off sc1
	global_store_dword v[32:33], v34, off offset:128 sc1
	v_fmamk_f32 v34, v162, 0x3f9837f0, v51
	v_lshl_add_u64 v[32:33], v[150:151], 0, v[84:85]
	global_store_dword v[32:33], v34, off sc1
	v_fmamk_f32 v34, v135, 0x3f9837f0, v35
	global_store_dword v[32:33], v34, off offset:128 sc1
	v_fmamk_f32 v34, v176, 0x3f9837f0, v52
	v_lshl_add_u64 v[32:33], v[150:151], 0, v[86:87]
	global_store_dword v[32:33], v34, off sc1
	v_fmamk_f32 v34, v175, 0x3f9837f0, v36
	global_store_dword v[32:33], v34, off offset:128 sc1
	v_fmamk_f32 v34, v174, 0x3f9837f0, v53
	v_lshl_add_u64 v[32:33], v[150:151], 0, v[88:89]
	global_store_dword v[32:33], v34, off sc1
	v_fmamk_f32 v34, v173, 0x3f9837f0, v37
	global_store_dword v[32:33], v34, off offset:128 sc1
	v_fmamk_f32 v34, v172, 0x3f9837f0, v54
	v_lshl_add_u64 v[32:33], v[150:151], 0, v[90:91]
	global_store_dword v[32:33], v34, off sc1
	v_fmamk_f32 v34, v171, 0x3f9837f0, v38
	global_store_dword v[32:33], v34, off offset:128 sc1
	v_fmamk_f32 v34, v170, 0x3f9837f0, v55
	v_lshl_add_u64 v[32:33], v[150:151], 0, v[92:93]
	global_store_dword v[32:33], v34, off sc1
	v_fmamk_f32 v34, v169, 0x3f9837f0, v39
	global_store_dword v[32:33], v34, off offset:128 sc1
	v_fmamk_f32 v34, v184, 0x3f9837f0, v56
	v_lshl_add_u64 v[32:33], v[150:151], 0, v[94:95]
	global_store_dword v[32:33], v34, off sc1
	v_fmamk_f32 v34, v183, 0x3f9837f0, v40
	global_store_dword v[32:33], v34, off offset:128 sc1
	v_fmamk_f32 v34, v182, 0x3f9837f0, v57
	v_lshl_add_u64 v[32:33], v[150:151], 0, v[96:97]
	global_store_dword v[32:33], v34, off sc1
	v_fmamk_f32 v34, v181, 0x3f9837f0, v41
	global_store_dword v[32:33], v34, off offset:128 sc1
	v_fmamk_f32 v34, v180, 0x3f9837f0, v58
	v_lshl_add_u64 v[32:33], v[150:151], 0, v[98:99]
	global_store_dword v[32:33], v34, off sc1
	v_fmamk_f32 v34, v179, 0x3f9837f0, v42
	global_store_dword v[32:33], v34, off offset:128 sc1
	v_fmamk_f32 v34, v178, 0x3f9837f0, v59
	v_lshl_add_u64 v[32:33], v[150:151], 0, v[100:101]
	global_store_dword v[32:33], v34, off sc1
	v_fmamk_f32 v34, v177, 0x3f9837f0, v43
	global_store_dword v[32:33], v34, off offset:128 sc1
	v_fmamk_f32 v34, v197, 0x3f9837f0, v60
	v_lshl_add_u64 v[32:33], v[150:151], 0, v[102:103]
	global_store_dword v[32:33], v34, off sc1
	v_fmamk_f32 v34, v191, 0x3f9837f0, v44
	global_store_dword v[32:33], v34, off offset:128 sc1
	v_fmamk_f32 v34, v190, 0x3f9837f0, v61
	v_lshl_add_u64 v[32:33], v[150:151], 0, v[104:105]
	global_store_dword v[32:33], v34, off sc1
	v_fmamk_f32 v34, v189, 0x3f9837f0, v45
	global_store_dword v[32:33], v34, off offset:128 sc1
	v_fmamk_f32 v34, v188, 0x3f9837f0, v62
	v_lshl_add_u64 v[32:33], v[150:151], 0, v[106:107]
	global_store_dword v[32:33], v34, off sc1
	v_fmamk_f32 v34, v187, 0x3f9837f0, v46
	global_store_dword v[32:33], v34, off offset:128 sc1
	v_fmac_f32_e32 v63, 0x3f9837f0, v186
	v_lshl_add_u64 v[32:33], v[150:151], 0, v[108:109]
	v_fmac_f32_e32 v47, 0x3f9837f0, v185
	global_store_dword v[32:33], v63, off sc1
	global_store_dword v[32:33], v47, off offset:128 sc1
	v_fmamk_f32 v16, v205, 0x3f9837f0, v16
	v_lshl_add_u64 v[32:33], v[150:151], 0, v[110:111]
	v_fmamk_f32 v0, v204, 0x3f9837f0, v0
	global_store_dword v[32:33], v16, off sc1
	global_store_dword v[32:33], v0, off offset:128 sc1
	v_fmamk_f32 v0, v203, 0x3f9837f0, v17
	v_lshl_add_u64 v[16:17], v[150:151], 0, v[112:113]
	global_store_dword v[16:17], v0, off sc1
	v_fmamk_f32 v0, v202, 0x3f9837f0, v1
	global_store_dword v[16:17], v0, off offset:128 sc1
	v_fmamk_f32 v16, v201, 0x3f9837f0, v18
	v_lshl_add_u64 v[0:1], v[150:151], 0, v[114:115]
	v_fmamk_f32 v2, v200, 0x3f9837f0, v2
	global_store_dword v[0:1], v16, off sc1
	global_store_dword v[0:1], v2, off offset:128 sc1
	v_fmamk_f32 v2, v199, 0x3f9837f0, v19
	v_lshl_add_u64 v[0:1], v[150:151], 0, v[116:117]
	global_store_dword v[0:1], v2, off sc1
	v_fmamk_f32 v2, v198, 0x3f9837f0, v3
	global_store_dword v[0:1], v2, off offset:128 sc1
	v_fmamk_f32 v2, v213, 0x3f9837f0, v20
	v_lshl_add_u64 v[0:1], v[150:151], 0, v[118:119]
	global_store_dword v[0:1], v2, off sc1
	v_fmamk_f32 v2, v212, 0x3f9837f0, v4
	global_store_dword v[0:1], v2, off offset:128 sc1
	v_fmamk_f32 v2, v211, 0x3f9837f0, v21
	v_lshl_add_u64 v[0:1], v[150:151], 0, v[120:121]
	global_store_dword v[0:1], v2, off sc1
	v_fmamk_f32 v2, v210, 0x3f9837f0, v5
	global_store_dword v[0:1], v2, off offset:128 sc1
	v_fmamk_f32 v2, v208, 0x3f9837f0, v22
	v_lshl_add_u64 v[0:1], v[150:151], 0, v[122:123]
	global_store_dword v[0:1], v2, off sc1
	v_fmamk_f32 v2, v209, 0x3f9837f0, v6
	global_store_dword v[0:1], v2, off offset:128 sc1
	v_fmamk_f32 v2, v207, 0x3f9837f0, v23
	v_lshl_add_u64 v[0:1], v[150:151], 0, v[124:125]
	global_store_dword v[0:1], v2, off sc1
	v_fmamk_f32 v2, v206, 0x3f9837f0, v7
	global_store_dword v[0:1], v2, off offset:128 sc1
	v_fmamk_f32 v2, v221, 0x3f9837f0, v24
	v_lshl_add_u64 v[0:1], v[150:151], 0, v[126:127]
	global_store_dword v[0:1], v2, off sc1
	v_fmamk_f32 v2, v220, 0x3f9837f0, v8
	global_store_dword v[0:1], v2, off offset:128 sc1
	v_fmamk_f32 v2, v219, 0x3f9837f0, v25
	v_lshl_add_u64 v[0:1], v[150:151], 0, v[136:137]
	global_store_dword v[0:1], v2, off sc1
	v_fmamk_f32 v2, v218, 0x3f9837f0, v9
	global_store_dword v[0:1], v2, off offset:128 sc1
	v_fmamk_f32 v2, v217, 0x3f9837f0, v26
	v_lshl_add_u64 v[0:1], v[150:151], 0, v[138:139]
	global_store_dword v[0:1], v2, off sc1
	v_fmamk_f32 v2, v216, 0x3f9837f0, v10
	global_store_dword v[0:1], v2, off offset:128 sc1
	v_fmamk_f32 v2, v215, 0x3f9837f0, v27
	v_lshl_add_u64 v[0:1], v[150:151], 0, v[140:141]
	global_store_dword v[0:1], v2, off sc1
	v_fmamk_f32 v2, v214, 0x3f9837f0, v11
	global_store_dword v[0:1], v2, off offset:128 sc1
	v_fmamk_f32 v2, v229, 0x3f9837f0, v28
	v_lshl_add_u64 v[0:1], v[150:151], 0, v[142:143]
	global_store_dword v[0:1], v2, off sc1
	v_fmamk_f32 v2, v228, 0x3f9837f0, v12
	global_store_dword v[0:1], v2, off offset:128 sc1
	v_fmamk_f32 v2, v227, 0x3f9837f0, v29
	v_lshl_add_u64 v[0:1], v[150:151], 0, v[144:145]
	global_store_dword v[0:1], v2, off sc1
	v_fmamk_f32 v2, v226, 0x3f9837f0, v13
	global_store_dword v[0:1], v2, off offset:128 sc1
	v_fmamk_f32 v2, v225, 0x3f9837f0, v30
	v_lshl_add_u64 v[0:1], v[150:151], 0, v[146:147]
	global_store_dword v[0:1], v2, off sc1
	v_fmamk_f32 v2, v224, 0x3f9837f0, v14
	s_add_i32 s87, s87, s38
	s_add_i32 s2, s2, s18
	s_add_i32 s3, s3, s16
	global_store_dword v[0:1], v2, off offset:128 sc1
	v_fmac_f32_e32 v31, 0x3f9837f0, v223
	v_lshl_add_u64 v[0:1], v[150:151], 0, v[148:149]
	v_fmac_f32_e32 v15, 0x3f9837f0, v222
	s_cmpk_gt_i32 s87, 0x7f
	global_store_dword v[0:1], v31, off sc1
	global_store_dword v[0:1], v15, off offset:128 sc1
	s_cbranch_scc1 .LBB0_2594
